# w2_wo_wout_transposes_moved_to_P2_idle_WGs
# baseline (speedup 1.0000x reference)
;     __device__ __forceinline__ float* ctl() const { return (float*)(ws + WS_CTL); }
;     __device__ __forceinline__ bf16_t* Win_t() const { return (bf16_t*)(ws + WS_WIN); }
;     __device__ __forceinline__ bf16_t* Wkv_t() const { return (bf16_t*)(ws + WS_WKV); }
;     __device__ __forceinline__ bf16_t* Wout_t() const { return (bf16_t*)(ws + WS_WOUT); }
;     __device__ __forceinline__ bf16_t* Wq_t() const { return (bf16_t*)(ws + WS_WQ); }
;     __device__ __forceinline__ bf16_t* Wo_t() const { return (bf16_t*)(ws + WS_WO); }
;     __device__ __forceinline__ bf16_t* W1_t() const { return (bf16_t*)(ws + WS_W1); }
;     __device__ __forceinline__ bf16_t* W2_t() const { return (bf16_t*)(ws + WS_W2); }
; __device__ __forceinline__ void p0_prologue(const Args& p, LAS unsigned char* lds, int G, int bid, int tid) {
;     ...
;     for (int it = gw; it < NITEMS; it += NGW) {
;         int r = it;
;         if (r < I_IN) { tr_item<1>(p.w_in(), DIN, p.Win_t(), DM, 0, scr, r / 48, r % 48, lane, nullptr, nullptr, nullptr, nullptr); continue; } r -= I_IN;
;         if (r < I_K) { tr_item<0>(p.xk_w(), DM, p.Wkv_t(), DM, 0, scr, r / 32, r % 32, lane, nullptr, nullptr, nullptr, nullptr); continue; } r -= I_K;
;         if (r < I_V) { tr_item<0>(p.xv_w(), DM, p.Wkv_t(), DM, DM, scr, r / 32, r % 32, lane, nullptr, nullptr, nullptr, nullptr); continue; } r -= I_V;
;         if (r < I_OUT) { tr_item<0>(p.w_out(), DM, p.Wout_t(), DM, 0, scr, r / 32, r % 32, lane, nullptr, nullptr, nullptr, nullptr); continue; } r -= I_OUT;
;         if (r < I_Q) { tr_item<2>(p.xq_w(), DM, p.Wq_t(), DM, 0, scr, r / 32, r % 32, lane, p.ln1_g(), p.ln1_b(), p.ctl() + CF_C1Q, p.ctl() + CF_C2Q); continue; } r -= I_Q;
;         if (r < I_O) { tr_item<0>(p.xo_w(), DM, p.Wo_t(), DM, 0, scr, r / 32, r % 32, lane, nullptr, nullptr, nullptr, nullptr); continue; } r -= I_O;
;         if (r < I_1) { tr_item<2>(p.w1(), DFF, p.W1_t(), DM, 0, scr, r / 128, r % 128, lane, p.ln2_g(), p.ln2_b(), p.ctl() + CF_C1H, p.ctl() + CF_C2H); continue; } r -= I_1;
;         tr_item<0>(p.w2(), DM, p.W2_t(), DFF, 0, scr, r / 32, r % 32, lane, nullptr, nullptr, nullptr, nullptr);
.LBB0_27:
	s_movk_i32 s4, 0x2ff
	v_cmp_lt_i32_e32 vcc, s4, v41
	s_and_saveexec_b64 s[4:5], vcc
	s_xor_b64 s[4:5], exec, s[4:5]
	s_cbranch_execz .LBB0_57
	s_movk_i32 s6, 0x4ff
	v_cmp_lt_u32_e32 vcc, s6, v41
	s_and_saveexec_b64 s[6:7], vcc
	s_xor_b64 s[6:7], exec, s[6:7]
	s_cbranch_execz .LBB0_54
	s_movk_i32 s8, 0x6ff
	v_cmp_lt_u32_e32 vcc, s8, v41
	s_and_saveexec_b64 s[8:9], vcc
	s_xor_b64 s[8:9], exec, s[8:9]
	s_cbranch_execz .LBB0_51
	s_movk_i32 s10, 0x7ff
	v_cmp_lt_u32_e32 vcc, s10, v41
	s_and_saveexec_b64 s[10:11], vcc
	s_xor_b64 s[10:11], exec, s[10:11]
	s_cbranch_execz .LBB0_48
	s_movk_i32 s12, 0x9ff
	v_cmp_lt_u32_e32 vcc, s12, v41
	s_and_saveexec_b64 s[12:13], vcc
	s_xor_b64 s[12:13], exec, s[12:13]
	s_cbranch_execz .LBB0_43
	s_movk_i32 s14, 0xbff
	v_cmp_lt_u32_e32 vcc, s14, v41
	s_and_saveexec_b64 s[14:15], vcc
	s_xor_b64 s[14:15], exec, s[14:15]
	s_cbranch_execz .LBB0_40
	s_movk_i32 s16, 0x13ff
	v_cmp_lt_u32_e32 vcc, s16, v41
	v_lshlrev_b32_e32 v0, 5, v41
	s_and_saveexec_b64 s[16:17], vcc
	s_xor_b64 s[16:17], exec, s[16:17]
	s_cbranch_execz .LBB0_35
	s_branch .LBB0_35

; #define LAS __attribute__((address_space(3)))
; __device__ __forceinline__ unsigned pk2(float lo, float hi) { f32x2v v = {lo, hi}; b16x2v b = __builtin_convertvector(v, b16x2v); return __builtin_bit_cast(unsigned, b); }
;     __device__ __forceinline__ bf16_t* Wo_t() const { return (bf16_t*)(ws + WS_WO); }
; template <int MODE>
; __device__ __forceinline__ void tr_item(const float* __restrict__ W, int N, bf16_t* WT, int ldk, int row_off, LAS float* scr, int kb, int nb, int lane,
;                                         const float* g, const float* b, float* c1, float* c2) {
;     const int k0 = 64 * kb, n0 = 32 * nb;
;     float tv[32];
; #pragma unroll
;     for (int i = 0; i < 32; ++i) tv[i] = __builtin_nontemporal_load(W + (size_t)(k0 + 2 * i + (lane >> 5)) * N + n0 + (lane & 31));
; #pragma unroll
;     for (int i = 0; i < 32; ++i) scr[(2 * i + (lane >> 5)) * 33 + (lane & 31)] = tv[i];
;     asm volatile("s_waitcnt lgkmcnt(0)" ::: "memory");
;     if (MODE == 2) {
;         const float* vec = (lane < 32) ? g : b; float s = 0.f;
; #pragma unroll 8
;         for (int k = 0; k < 64; ++k) s += vec[k0 + k] * scr[k * 33 + (lane & 31)];
;         atomicAdd(((lane < 32) ? c1 : c2) + n0 + (lane & 31), s);
;     }
;     const int c = lane & 7;
;     float gs[8];
; #pragma unroll
;     for (int i = 0; i < 8; ++i) gs[i] = (MODE == 2) ? g[k0 + 8 * c + i] : 1.0f;
; #pragma unroll
;     for (int j = 0; j < 4; ++j) { const int n = (lane >> 3) + 8 * j; const LAS float* s = scr + (8 * c) * 33 + n;
;         u32x4 o; o.x = pk2(s[0 * 33] * gs[0], s[1 * 33] * gs[1]); o.y = pk2(s[2 * 33] * gs[2], s[3 * 33] * gs[3]); o.z = pk2(s[4 * 33] * gs[4], s[5 * 33] * gs[5]); o.w = pk2(s[6 * 33] * gs[6], s[7 * 33] * gs[7]);
;         const int dr = (MODE == 1) ? win_dest(n0 + n) : (n0 + n);
;         *(u32x4*)(WT + (size_t)(row_off + dr) * ldk + k0 + 8 * c) = o; }
; __device__ __forceinline__ void p0_prologue(const Args& p, LAS unsigned char* lds, int G, int bid, int tid) {
;     ...
;         if (r < I_O) { tr_item<0>(p.xo_w(), DM, p.Wo_t(), DM, 0, scr, r / 32, r % 32, lane, nullptr, nullptr, nullptr, nullptr); continue; } r -= I_O;
.LBB0_40:
	s_andn2_saveexec_b64 s[14:15], s[14:15]
	s_cbranch_execz .LBB0_42
	s_branch .LBB0_42

; #define LAS __attribute__((address_space(3)))
; __device__ __forceinline__ unsigned pk2(float lo, float hi) { f32x2v v = {lo, hi}; b16x2v b = __builtin_convertvector(v, b16x2v); return __builtin_bit_cast(unsigned, b); }
;     __device__ __forceinline__ bf16_t* Wout_t() const { return (bf16_t*)(ws + WS_WOUT); }
; template <int MODE>
; __device__ __forceinline__ void tr_item(const float* __restrict__ W, int N, bf16_t* WT, int ldk, int row_off, LAS float* scr, int kb, int nb, int lane,
;                                         const float* g, const float* b, float* c1, float* c2) {
;     const int k0 = 64 * kb, n0 = 32 * nb;
;     float tv[32];
; #pragma unroll
;     for (int i = 0; i < 32; ++i) tv[i] = __builtin_nontemporal_load(W + (size_t)(k0 + 2 * i + (lane >> 5)) * N + n0 + (lane & 31));
; #pragma unroll
;     for (int i = 0; i < 32; ++i) scr[(2 * i + (lane >> 5)) * 33 + (lane & 31)] = tv[i];
;     asm volatile("s_waitcnt lgkmcnt(0)" ::: "memory");
;     if (MODE == 2) {
;         const float* vec = (lane < 32) ? g : b; float s = 0.f;
; #pragma unroll 8
;         for (int k = 0; k < 64; ++k) s += vec[k0 + k] * scr[k * 33 + (lane & 31)];
;         atomicAdd(((lane < 32) ? c1 : c2) + n0 + (lane & 31), s);
;     }
;     const int c = lane & 7;
;     float gs[8];
; #pragma unroll
;     for (int i = 0; i < 8; ++i) gs[i] = (MODE == 2) ? g[k0 + 8 * c + i] : 1.0f;
; #pragma unroll
;     for (int j = 0; j < 4; ++j) { const int n = (lane >> 3) + 8 * j; const LAS float* s = scr + (8 * c) * 33 + n;
;         u32x4 o; o.x = pk2(s[0 * 33] * gs[0], s[1 * 33] * gs[1]); o.y = pk2(s[2 * 33] * gs[2], s[3 * 33] * gs[3]); o.z = pk2(s[4 * 33] * gs[4], s[5 * 33] * gs[5]); o.w = pk2(s[6 * 33] * gs[6], s[7 * 33] * gs[7]);
;         const int dr = (MODE == 1) ? win_dest(n0 + n) : (n0 + n);
;         *(u32x4*)(WT + (size_t)(row_off + dr) * ldk + k0 + 8 * c) = o; }
; __device__ __forceinline__ void p0_prologue(const Args& p, LAS unsigned char* lds, int G, int bid, int tid) {
;     ...
;         if (r < I_OUT) { tr_item<0>(p.w_out(), DM, p.Wout_t(), DM, 0, scr, r / 32, r % 32, lane, nullptr, nullptr, nullptr, nullptr); continue; } r -= I_OUT;
.LBB0_48:
	s_andn2_saveexec_b64 s[10:11], s[10:11]
	s_cbranch_execz .LBB0_50
	s_branch .LBB0_50

; template <int MODE>
; __device__ __forceinline__ void tr_item(const float* __restrict__ W, int N, bf16_t* WT, int ldk, int row_off, LAS float* scr, int kb, int nb, int lane,
;                                         const float* g, const float* b, float* c1, float* c2) {
;     const int k0 = 64 * kb, n0 = 32 * nb;
;     float tv[32];
; #pragma unroll
;     for (int i = 0; i < 32; ++i) tv[i] = __builtin_nontemporal_load(W + (size_t)(k0 + 2 * i + (lane >> 5)) * N + n0 + (lane & 31));
; #pragma unroll
;     for (int i = 0; i < 32; ++i) scr[(2 * i + (lane >> 5)) * 33 + (lane & 31)] = tv[i];
;     asm volatile("s_waitcnt lgkmcnt(0)" ::: "memory");
;     if (MODE == 2) {
;         const float* vec = (lane < 32) ? g : b; float s = 0.f;
; #pragma unroll 8
;         for (int k = 0; k < 64; ++k) s += vec[k0 + k] * scr[k * 33 + (lane & 31)];
;         atomicAdd(((lane < 32) ? c1 : c2) + n0 + (lane & 31), s);
;     }
;     const int c = lane & 7;
;     float gs[8];
; #pragma unroll
;     for (int i = 0; i < 8; ++i) gs[i] = (MODE == 2) ? g[k0 + 8 * c + i] : 1.0f;
; #pragma unroll
;     for (int j = 0; j < 4; ++j) { const int n = (lane >> 3) + 8 * j; const LAS float* s = scr + (8 * c) * 33 + n;
;         u32x4 o; o.x = pk2(s[0 * 33] * gs[0], s[1 * 33] * gs[1]); o.y = pk2(s[2 * 33] * gs[2], s[3 * 33] * gs[3]); o.z = pk2(s[4 * 33] * gs[4], s[5 * 33] * gs[5]); o.w = pk2(s[6 * 33] * gs[6], s[7 * 33] * gs[7]);
;         const int dr = (MODE == 1) ? win_dest(n0 + n) : (n0 + n);
;         *(u32x4*)(WT + (size_t)(row_off + dr) * ldk + k0 + 8 * c) = o; }
; __device__ __forceinline__ void p0_prologue(const Args& p, LAS unsigned char* lds, int G, int bid, int tid) {
;     ...
;     for (int it = gw; it < NITEMS; it += NGW) {
;         int r = it;
;         if (r < I_IN) { tr_item<1>(p.w_in(), DIN, p.Win_t(), DM, 0, scr, r / 48, r % 48, lane, nullptr, nullptr, nullptr, nullptr); continue; } r -= I_IN;
;         if (r < I_K) { tr_item<0>(p.xk_w(), DM, p.Wkv_t(), DM, 0, scr, r / 32, r % 32, lane, nullptr, nullptr, nullptr, nullptr); continue; } r -= I_K;
;         if (r < I_V) { tr_item<0>(p.xv_w(), DM, p.Wkv_t(), DM, DM, scr, r / 32, r % 32, lane, nullptr, nullptr, nullptr, nullptr); continue; } r -= I_V;
;         if (r < I_OUT) { tr_item<0>(p.w_out(), DM, p.Wout_t(), DM, 0, scr, r / 32, r % 32, lane, nullptr, nullptr, nullptr, nullptr); continue; } r -= I_OUT;
.Ltr2_vcu:
	s_cmp_lt_u32 s1, 64
	s_cbranch_scc1 .Ltr2_skip
	s_sub_u32 s1, s1, 64
	v_lshrrev_b32_e32 v32, 6, v192
	v_and_b32_e32 v33, 63, v192
	v_readfirstlane_b32 s0, v32
	s_load_dwordx2 s[8:9], s[100:101], 0xd0
	s_load_dwordx2 s[62:63], s[100:101], 0xa8
	s_load_dwordx2 s[64:65], s[100:101], 0x78
	s_nop 3
	s_lshl_b32 s1, s1, 3
	s_add_u32 s10, s1, s0
	s_sub_u32 s11, s96, 64
	s_lshl_b32 s11, s11, 3
	s_lshl_b32 s0, s0, 14
	v_lshrrev_b32_e32 v38, 5, v33
	v_and_b32_e32 v39, 31, v33
	v_lshlrev_b32_e32 v34, 12, v38
	v_lshl_add_u32 v34, v39, 2, v34
	v_mul_u32_u24_e32 v35, 0x84, v38
	v_lshl_add_u32 v35, v39, 2, v35
	v_add_u32_e32 v35, s0, v35
	v_and_b32_e32 v38, 7, v33
	v_lshrrev_b32_e32 v39, 3, v33
	v_mul_u32_u24_e32 v36, 0x420, v38
	v_lshl_add_u32 v36, v39, 2, v36
	v_add_u32_e32 v36, s0, v36
	v_lshlrev_b32_e32 v37, 13, v39
	v_lshl_add_u32 v37, v38, 4, v37
	v_lshlrev_b32_e32 v84, 11, v39
	v_lshl_add_u32 v84, v38, 4, v84
	s_waitcnt lgkmcnt(0)
.Ltr2_loop:
	s_cmp_ge_u32 s10, 0xb00
	s_cbranch_scc1 .Ltr2_skip
	s_cmp_ge_u32 s10, 0x800
	s_cbranch_scc1 .Ltr2_not_w2
	s_lshr_b32 s0, s10, 5
	s_and_b32 s1, s10, 31
	s_mul_i32 s12, s0, 0x40000
	s_lshl_b32 s13, s1, 7
	s_add_u32 s12, s12, s13
	s_add_u32 s12, s8, s12
	s_addc_u32 s13, s9, 0
	global_load_dword v40, v34, s[12:13] nt
	s_add_u32 s12, s12, 0x2000
	s_addc_u32 s13, s13, 0
	global_load_dword v41, v34, s[12:13] nt
	s_add_u32 s12, s12, 0x2000
	s_addc_u32 s13, s13, 0
	global_load_dword v42, v34, s[12:13] nt
	s_add_u32 s12, s12, 0x2000
	s_addc_u32 s13, s13, 0
	global_load_dword v43, v34, s[12:13] nt
	s_add_u32 s12, s12, 0x2000
	s_addc_u32 s13, s13, 0
	global_load_dword v44, v34, s[12:13] nt
	s_add_u32 s12, s12, 0x2000
	s_addc_u32 s13, s13, 0
	global_load_dword v45, v34, s[12:13] nt
	s_add_u32 s12, s12, 0x2000
	s_addc_u32 s13, s13, 0
	global_load_dword v46, v34, s[12:13] nt
	s_add_u32 s12, s12, 0x2000
	s_addc_u32 s13, s13, 0
	global_load_dword v47, v34, s[12:13] nt
	s_add_u32 s12, s12, 0x2000
	s_addc_u32 s13, s13, 0
	global_load_dword v48, v34, s[12:13] nt
	s_add_u32 s12, s12, 0x2000
	s_addc_u32 s13, s13, 0
	global_load_dword v49, v34, s[12:13] nt
	s_add_u32 s12, s12, 0x2000
	s_addc_u32 s13, s13, 0
	global_load_dword v50, v34, s[12:13] nt
	s_add_u32 s12, s12, 0x2000
	s_addc_u32 s13, s13, 0
	global_load_dword v51, v34, s[12:13] nt
	s_add_u32 s12, s12, 0x2000
	s_addc_u32 s13, s13, 0
	global_load_dword v52, v34, s[12:13] nt
	s_add_u32 s12, s12, 0x2000
	s_addc_u32 s13, s13, 0
	global_load_dword v53, v34, s[12:13] nt
	s_add_u32 s12, s12, 0x2000
	s_addc_u32 s13, s13, 0
	global_load_dword v54, v34, s[12:13] nt
	s_add_u32 s12, s12, 0x2000
	s_addc_u32 s13, s13, 0
	global_load_dword v55, v34, s[12:13] nt
	s_add_u32 s12, s12, 0x2000
	s_addc_u32 s13, s13, 0
	global_load_dword v56, v34, s[12:13] nt
	s_add_u32 s12, s12, 0x2000
	s_addc_u32 s13, s13, 0
	global_load_dword v57, v34, s[12:13] nt
	s_add_u32 s12, s12, 0x2000
	s_addc_u32 s13, s13, 0
	global_load_dword v58, v34, s[12:13] nt
	s_add_u32 s12, s12, 0x2000
	s_addc_u32 s13, s13, 0
	global_load_dword v59, v34, s[12:13] nt
	s_add_u32 s12, s12, 0x2000
	s_addc_u32 s13, s13, 0
	global_load_dword v60, v34, s[12:13] nt
	s_add_u32 s12, s12, 0x2000
	s_addc_u32 s13, s13, 0
	global_load_dword v61, v34, s[12:13] nt
	s_add_u32 s12, s12, 0x2000
	s_addc_u32 s13, s13, 0
	global_load_dword v62, v34, s[12:13] nt
	s_add_u32 s12, s12, 0x2000
	s_addc_u32 s13, s13, 0
	global_load_dword v63, v34, s[12:13] nt
	s_add_u32 s12, s12, 0x2000
	s_addc_u32 s13, s13, 0
	global_load_dword v64, v34, s[12:13] nt
	s_add_u32 s12, s12, 0x2000
	s_addc_u32 s13, s13, 0
	global_load_dword v65, v34, s[12:13] nt
	s_add_u32 s12, s12, 0x2000
	s_addc_u32 s13, s13, 0
	global_load_dword v66, v34, s[12:13] nt
	s_add_u32 s12, s12, 0x2000
	s_addc_u32 s13, s13, 0
	global_load_dword v67, v34, s[12:13] nt
	s_add_u32 s12, s12, 0x2000
	s_addc_u32 s13, s13, 0
	global_load_dword v68, v34, s[12:13] nt
	s_add_u32 s12, s12, 0x2000
	s_addc_u32 s13, s13, 0
	global_load_dword v69, v34, s[12:13] nt
	s_add_u32 s12, s12, 0x2000
	s_addc_u32 s13, s13, 0
	global_load_dword v70, v34, s[12:13] nt
	s_add_u32 s12, s12, 0x2000
	s_addc_u32 s13, s13, 0
	global_load_dword v71, v34, s[12:13] nt
	s_mul_i32 s12, s1, 0x40000
	s_lshl_b32 s13, s0, 7
	s_add_u32 s12, s12, s13
	s_add_u32 s12, s12, 0x1700000
	s_add_u32 s12, s58, s12
	s_addc_u32 s13, s59, 0
	s_waitcnt vmcnt(31)
	ds_write_b32 v35, v40
	s_waitcnt vmcnt(30)
	ds_write_b32 v35, v41 offset:264
	s_waitcnt vmcnt(29)
	ds_write_b32 v35, v42 offset:528
	s_waitcnt vmcnt(28)
	ds_write_b32 v35, v43 offset:792
	s_waitcnt vmcnt(27)
	ds_write_b32 v35, v44 offset:1056
	s_waitcnt vmcnt(26)
	ds_write_b32 v35, v45 offset:1320
	s_waitcnt vmcnt(25)
	ds_write_b32 v35, v46 offset:1584
	s_waitcnt vmcnt(24)
	ds_write_b32 v35, v47 offset:1848
	s_waitcnt vmcnt(23)
	ds_write_b32 v35, v48 offset:2112
	s_waitcnt vmcnt(22)
	ds_write_b32 v35, v49 offset:2376
	s_waitcnt vmcnt(21)
	ds_write_b32 v35, v50 offset:2640
	s_waitcnt vmcnt(20)
	ds_write_b32 v35, v51 offset:2904
	s_waitcnt vmcnt(19)
	ds_write_b32 v35, v52 offset:3168
	s_waitcnt vmcnt(18)
	ds_write_b32 v35, v53 offset:3432
	s_waitcnt vmcnt(17)
	ds_write_b32 v35, v54 offset:3696
	s_waitcnt vmcnt(16)
	ds_write_b32 v35, v55 offset:3960
	s_waitcnt vmcnt(15)
	ds_write_b32 v35, v56 offset:4224
	s_waitcnt vmcnt(14)
	ds_write_b32 v35, v57 offset:4488
	s_waitcnt vmcnt(13)
	ds_write_b32 v35, v58 offset:4752
	s_waitcnt vmcnt(12)
	ds_write_b32 v35, v59 offset:5016
	s_waitcnt vmcnt(11)
	ds_write_b32 v35, v60 offset:5280
	s_waitcnt vmcnt(10)
	ds_write_b32 v35, v61 offset:5544
	s_waitcnt vmcnt(9)
	ds_write_b32 v35, v62 offset:5808
	s_waitcnt vmcnt(8)
	ds_write_b32 v35, v63 offset:6072
	s_waitcnt vmcnt(7)
; #define LAS __attribute__((address_space(3)))
; __device__ __forceinline__ unsigned pk2(float lo, float hi) { f32x2v v = {lo, hi}; b16x2v b = __builtin_convertvector(v, b16x2v); return __builtin_bit_cast(unsigned, b); }
;     __device__ __forceinline__ bf16_t* Wo_t() const { return (bf16_t*)(ws + WS_WO); }
; template <int MODE>
; __device__ __forceinline__ void tr_item(const float* __restrict__ W, int N, bf16_t* WT, int ldk, int row_off, LAS float* scr, int kb, int nb, int lane,
;                                         const float* g, const float* b, float* c1, float* c2) {
;     const int k0 = 64 * kb, n0 = 32 * nb;
;     float tv[32];
; #pragma unroll
;     for (int i = 0; i < 32; ++i) tv[i] = __builtin_nontemporal_load(W + (size_t)(k0 + 2 * i + (lane >> 5)) * N + n0 + (lane & 31));
; #pragma unroll
;     for (int i = 0; i < 32; ++i) scr[(2 * i + (lane >> 5)) * 33 + (lane & 31)] = tv[i];
;     asm volatile("s_waitcnt lgkmcnt(0)" ::: "memory");
;     if (MODE == 2) {
;         const float* vec = (lane < 32) ? g : b; float s = 0.f;
; #pragma unroll 8
;         for (int k = 0; k < 64; ++k) s += vec[k0 + k] * scr[k * 33 + (lane & 31)];
;         atomicAdd(((lane < 32) ? c1 : c2) + n0 + (lane & 31), s);
;     }
;     const int c = lane & 7;
;     float gs[8];
; #pragma unroll
;     for (int i = 0; i < 8; ++i) gs[i] = (MODE == 2) ? g[k0 + 8 * c + i] : 1.0f;
; #pragma unroll
;     for (int j = 0; j < 4; ++j) { const int n = (lane >> 3) + 8 * j; const LAS float* s = scr + (8 * c) * 33 + n;
;         u32x4 o; o.x = pk2(s[0 * 33] * gs[0], s[1 * 33] * gs[1]); o.y = pk2(s[2 * 33] * gs[2], s[3 * 33] * gs[3]); o.z = pk2(s[4 * 33] * gs[4], s[5 * 33] * gs[5]); o.w = pk2(s[6 * 33] * gs[6], s[7 * 33] * gs[7]);
;         const int dr = (MODE == 1) ? win_dest(n0 + n) : (n0 + n);
;         *(u32x4*)(WT + (size_t)(row_off + dr) * ldk + k0 + 8 * c) = o; }
; __device__ __forceinline__ void p0_prologue(const Args& p, LAS unsigned char* lds, int G, int bid, int tid) {
;     ...
;         if (r < I_O) { tr_item<0>(p.xo_w(), DM, p.Wo_t(), DM, 0, scr, r / 32, r % 32, lane, nullptr, nullptr, nullptr, nullptr); continue; } r -= I_O;
	ds_write_b32 v35, v64 offset:6336
	s_waitcnt vmcnt(6)
	ds_write_b32 v35, v65 offset:6600
	s_waitcnt vmcnt(5)
	ds_write_b32 v35, v66 offset:6864
	s_waitcnt vmcnt(4)
	ds_write_b32 v35, v67 offset:7128
	s_waitcnt vmcnt(3)
	ds_write_b32 v35, v68 offset:7392
	s_waitcnt vmcnt(2)
	ds_write_b32 v35, v69 offset:7656
	s_waitcnt vmcnt(1)
	ds_write_b32 v35, v70 offset:7920
	s_waitcnt vmcnt(0)
	ds_write_b32 v35, v71 offset:8184
	s_waitcnt lgkmcnt(0)
	ds_read2_b32 v[72:73], v36 offset1:33
	ds_read2_b32 v[74:75], v36 offset0:66 offset1:99
	ds_read2_b32 v[76:77], v36 offset0:132 offset1:165
	ds_read2_b32 v[78:79], v36 offset0:198 offset1:231
	s_waitcnt lgkmcnt(0)
	v_cvt_pk_bf16_f32 v80, v72, v73
	v_cvt_pk_bf16_f32 v81, v74, v75
	v_cvt_pk_bf16_f32 v82, v76, v77
	v_cvt_pk_bf16_f32 v83, v78, v79
	global_store_dwordx4 v37, v[80:83], s[12:13]
	s_add_u32 s12, s12, 0x10000
	s_addc_u32 s13, s13, 0
	ds_read2_b32 v[72:73], v36 offset0:8 offset1:41
	ds_read2_b32 v[74:75], v36 offset0:74 offset1:107
	ds_read2_b32 v[76:77], v36 offset0:140 offset1:173
	ds_read2_b32 v[78:79], v36 offset0:206 offset1:239
	s_waitcnt lgkmcnt(0)
	v_cvt_pk_bf16_f32 v80, v72, v73
	v_cvt_pk_bf16_f32 v81, v74, v75
	v_cvt_pk_bf16_f32 v82, v76, v77
	v_cvt_pk_bf16_f32 v83, v78, v79
	global_store_dwordx4 v37, v[80:83], s[12:13]
	s_add_u32 s12, s12, 0x10000
	s_addc_u32 s13, s13, 0
	ds_read2_b32 v[72:73], v36 offset0:16 offset1:49
	ds_read2_b32 v[74:75], v36 offset0:82 offset1:115
	ds_read2_b32 v[76:77], v36 offset0:148 offset1:181
	ds_read2_b32 v[78:79], v36 offset0:214 offset1:247
	s_waitcnt lgkmcnt(0)
	v_cvt_pk_bf16_f32 v80, v72, v73
	v_cvt_pk_bf16_f32 v81, v74, v75
	v_cvt_pk_bf16_f32 v82, v76, v77
	v_cvt_pk_bf16_f32 v83, v78, v79
	global_store_dwordx4 v37, v[80:83], s[12:13]
	s_add_u32 s12, s12, 0x10000
	s_addc_u32 s13, s13, 0
	ds_read2_b32 v[72:73], v36 offset0:24 offset1:57
	ds_read2_b32 v[74:75], v36 offset0:90 offset1:123
	ds_read2_b32 v[76:77], v36 offset0:156 offset1:189
	ds_read2_b32 v[78:79], v36 offset0:222 offset1:255
	s_waitcnt lgkmcnt(0)
	v_cvt_pk_bf16_f32 v80, v72, v73
	v_cvt_pk_bf16_f32 v81, v74, v75
	v_cvt_pk_bf16_f32 v82, v76, v77
	v_cvt_pk_bf16_f32 v83, v78, v79
	global_store_dwordx4 v37, v[80:83], s[12:13]
	s_branch .Ltr2_next
.Ltr2_not_w2:
	s_cmp_ge_u32 s10, 0xa00
	s_cbranch_scc1 .Ltr2_wout
	s_sub_u32 s66, s10, 0x800
	s_lshr_b32 s0, s66, 5
	s_and_b32 s1, s66, 31
	s_mul_i32 s12, s0, 0x40000
	s_lshl_b32 s13, s1, 7
	s_add_u32 s12, s12, s13
	s_add_u32 s12, s62, s12
	s_addc_u32 s13, s63, 0
	global_load_dword v40, v34, s[12:13] nt
	s_add_u32 s12, s12, 0x2000
	s_addc_u32 s13, s13, 0
	global_load_dword v41, v34, s[12:13] nt
	s_add_u32 s12, s12, 0x2000
	s_addc_u32 s13, s13, 0
	global_load_dword v42, v34, s[12:13] nt
	s_add_u32 s12, s12, 0x2000
	s_addc_u32 s13, s13, 0
	global_load_dword v43, v34, s[12:13] nt
	s_add_u32 s12, s12, 0x2000
	s_addc_u32 s13, s13, 0
	global_load_dword v44, v34, s[12:13] nt
	s_add_u32 s12, s12, 0x2000
	s_addc_u32 s13, s13, 0
	global_load_dword v45, v34, s[12:13] nt
	s_add_u32 s12, s12, 0x2000
	s_addc_u32 s13, s13, 0
	global_load_dword v46, v34, s[12:13] nt
	s_add_u32 s12, s12, 0x2000
	s_addc_u32 s13, s13, 0
	global_load_dword v47, v34, s[12:13] nt
	s_add_u32 s12, s12, 0x2000
	s_addc_u32 s13, s13, 0
	global_load_dword v48, v34, s[12:13] nt
	s_add_u32 s12, s12, 0x2000
	s_addc_u32 s13, s13, 0
	global_load_dword v49, v34, s[12:13] nt
	s_add_u32 s12, s12, 0x2000
	s_addc_u32 s13, s13, 0
	global_load_dword v50, v34, s[12:13] nt
	s_add_u32 s12, s12, 0x2000
	s_addc_u32 s13, s13, 0
	global_load_dword v51, v34, s[12:13] nt
	s_add_u32 s12, s12, 0x2000
	s_addc_u32 s13, s13, 0
	global_load_dword v52, v34, s[12:13] nt
	s_add_u32 s12, s12, 0x2000
	s_addc_u32 s13, s13, 0
	global_load_dword v53, v34, s[12:13] nt
	s_add_u32 s12, s12, 0x2000
	s_addc_u32 s13, s13, 0
	global_load_dword v54, v34, s[12:13] nt
	s_add_u32 s12, s12, 0x2000
	s_addc_u32 s13, s13, 0
	global_load_dword v55, v34, s[12:13] nt
	s_add_u32 s12, s12, 0x2000
	s_addc_u32 s13, s13, 0
	global_load_dword v56, v34, s[12:13] nt
	s_add_u32 s12, s12, 0x2000
	s_addc_u32 s13, s13, 0
	global_load_dword v57, v34, s[12:13] nt
	s_add_u32 s12, s12, 0x2000
	s_addc_u32 s13, s13, 0
	global_load_dword v58, v34, s[12:13] nt
	s_add_u32 s12, s12, 0x2000
	s_addc_u32 s13, s13, 0
	global_load_dword v59, v34, s[12:13] nt
	s_add_u32 s12, s12, 0x2000
	s_addc_u32 s13, s13, 0
	global_load_dword v60, v34, s[12:13] nt
	s_add_u32 s12, s12, 0x2000
	s_addc_u32 s13, s13, 0
	global_load_dword v61, v34, s[12:13] nt
	s_add_u32 s12, s12, 0x2000
	s_addc_u32 s13, s13, 0
	global_load_dword v62, v34, s[12:13] nt
	s_add_u32 s12, s12, 0x2000
	s_addc_u32 s13, s13, 0
	global_load_dword v63, v34, s[12:13] nt
	s_add_u32 s12, s12, 0x2000
	s_addc_u32 s13, s13, 0
	global_load_dword v64, v34, s[12:13] nt
	s_add_u32 s12, s12, 0x2000
	s_addc_u32 s13, s13, 0
	global_load_dword v65, v34, s[12:13] nt
	s_add_u32 s12, s12, 0x2000
	s_addc_u32 s13, s13, 0
	global_load_dword v66, v34, s[12:13] nt
	s_add_u32 s12, s12, 0x2000
	s_addc_u32 s13, s13, 0
	global_load_dword v67, v34, s[12:13] nt
	s_add_u32 s12, s12, 0x2000
	s_addc_u32 s13, s13, 0
	global_load_dword v68, v34, s[12:13] nt
	s_add_u32 s12, s12, 0x2000
	s_addc_u32 s13, s13, 0
	global_load_dword v69, v34, s[12:13] nt
	s_add_u32 s12, s12, 0x2000
	s_addc_u32 s13, s13, 0
	global_load_dword v70, v34, s[12:13] nt
	s_add_u32 s12, s12, 0x2000
	s_addc_u32 s13, s13, 0
	global_load_dword v71, v34, s[12:13] nt
	s_mul_i32 s12, s1, 0x10000
	s_lshl_b32 s13, s0, 7
	s_add_u32 s12, s12, s13
	s_add_u32 s12, s12, 0xd00000
	s_add_u32 s12, s58, s12
	s_addc_u32 s13, s59, 0
	s_waitcnt vmcnt(31)
	ds_write_b32 v35, v40
	s_waitcnt vmcnt(30)
; #define LAS __attribute__((address_space(3)))
; __device__ __forceinline__ unsigned pk2(float lo, float hi) { f32x2v v = {lo, hi}; b16x2v b = __builtin_convertvector(v, b16x2v); return __builtin_bit_cast(unsigned, b); }
; template <int MODE>
; __device__ __forceinline__ void tr_item(const float* __restrict__ W, int N, bf16_t* WT, int ldk, int row_off, LAS float* scr, int kb, int nb, int lane,
;                                         const float* g, const float* b, float* c1, float* c2) {
;     ...
;     for (int i = 0; i < 32; ++i) scr[(2 * i + (lane >> 5)) * 33 + (lane & 31)] = tv[i];
;     asm volatile("s_waitcnt lgkmcnt(0)" ::: "memory");
;     if (MODE == 2) {
;         const float* vec = (lane < 32) ? g : b; float s = 0.f;
; #pragma unroll 8
;         for (int k = 0; k < 64; ++k) s += vec[k0 + k] * scr[k * 33 + (lane & 31)];
;         atomicAdd(((lane < 32) ? c1 : c2) + n0 + (lane & 31), s);
;     }
;     const int c = lane & 7;
;     float gs[8];
; #pragma unroll
;     for (int i = 0; i < 8; ++i) gs[i] = (MODE == 2) ? g[k0 + 8 * c + i] : 1.0f;
; #pragma unroll
;     for (int j = 0; j < 4; ++j) { const int n = (lane >> 3) + 8 * j; const LAS float* s = scr + (8 * c) * 33 + n;
;         u32x4 o; o.x = pk2(s[0 * 33] * gs[0], s[1 * 33] * gs[1]); o.y = pk2(s[2 * 33] * gs[2], s[3 * 33] * gs[3]); o.z = pk2(s[4 * 33] * gs[4], s[5 * 33] * gs[5]); o.w = pk2(s[6 * 33] * gs[6], s[7 * 33] * gs[7]);
;         const int dr = (MODE == 1) ? win_dest(n0 + n) : (n0 + n);
;         *(u32x4*)(WT + (size_t)(row_off + dr) * ldk + k0 + 8 * c) = o; }
	ds_write_b32 v35, v41 offset:264
	s_waitcnt vmcnt(29)
	ds_write_b32 v35, v42 offset:528
	s_waitcnt vmcnt(28)
	ds_write_b32 v35, v43 offset:792
	s_waitcnt vmcnt(27)
	ds_write_b32 v35, v44 offset:1056
	s_waitcnt vmcnt(26)
	ds_write_b32 v35, v45 offset:1320
	s_waitcnt vmcnt(25)
	ds_write_b32 v35, v46 offset:1584
	s_waitcnt vmcnt(24)
	ds_write_b32 v35, v47 offset:1848
	s_waitcnt vmcnt(23)
	ds_write_b32 v35, v48 offset:2112
	s_waitcnt vmcnt(22)
	ds_write_b32 v35, v49 offset:2376
	s_waitcnt vmcnt(21)
	ds_write_b32 v35, v50 offset:2640
	s_waitcnt vmcnt(20)
	ds_write_b32 v35, v51 offset:2904
	s_waitcnt vmcnt(19)
	ds_write_b32 v35, v52 offset:3168
	s_waitcnt vmcnt(18)
	ds_write_b32 v35, v53 offset:3432
	s_waitcnt vmcnt(17)
	ds_write_b32 v35, v54 offset:3696
	s_waitcnt vmcnt(16)
	ds_write_b32 v35, v55 offset:3960
	s_waitcnt vmcnt(15)
	ds_write_b32 v35, v56 offset:4224
	s_waitcnt vmcnt(14)
	ds_write_b32 v35, v57 offset:4488
	s_waitcnt vmcnt(13)
	ds_write_b32 v35, v58 offset:4752
	s_waitcnt vmcnt(12)
	ds_write_b32 v35, v59 offset:5016
	s_waitcnt vmcnt(11)
	ds_write_b32 v35, v60 offset:5280
	s_waitcnt vmcnt(10)
	ds_write_b32 v35, v61 offset:5544
	s_waitcnt vmcnt(9)
	ds_write_b32 v35, v62 offset:5808
	s_waitcnt vmcnt(8)
	ds_write_b32 v35, v63 offset:6072
	s_waitcnt vmcnt(7)
	ds_write_b32 v35, v64 offset:6336
	s_waitcnt vmcnt(6)
	ds_write_b32 v35, v65 offset:6600
	s_waitcnt vmcnt(5)
	ds_write_b32 v35, v66 offset:6864
	s_waitcnt vmcnt(4)
	ds_write_b32 v35, v67 offset:7128
	s_waitcnt vmcnt(3)
	ds_write_b32 v35, v68 offset:7392
	s_waitcnt vmcnt(2)
	ds_write_b32 v35, v69 offset:7656
	s_waitcnt vmcnt(1)
	ds_write_b32 v35, v70 offset:7920
	s_waitcnt vmcnt(0)
	ds_write_b32 v35, v71 offset:8184
	s_waitcnt lgkmcnt(0)
	ds_read2_b32 v[72:73], v36 offset1:33
	ds_read2_b32 v[74:75], v36 offset0:66 offset1:99
	ds_read2_b32 v[76:77], v36 offset0:132 offset1:165
	ds_read2_b32 v[78:79], v36 offset0:198 offset1:231
	s_waitcnt lgkmcnt(0)
	v_cvt_pk_bf16_f32 v80, v72, v73
	v_cvt_pk_bf16_f32 v81, v74, v75
	v_cvt_pk_bf16_f32 v82, v76, v77
	v_cvt_pk_bf16_f32 v83, v78, v79
	global_store_dwordx4 v84, v[80:83], s[12:13]
	s_add_u32 s12, s12, 0x4000
	s_addc_u32 s13, s13, 0
	ds_read2_b32 v[72:73], v36 offset0:8 offset1:41
	ds_read2_b32 v[74:75], v36 offset0:74 offset1:107
	ds_read2_b32 v[76:77], v36 offset0:140 offset1:173
	ds_read2_b32 v[78:79], v36 offset0:206 offset1:239
	s_waitcnt lgkmcnt(0)
	v_cvt_pk_bf16_f32 v80, v72, v73
	v_cvt_pk_bf16_f32 v81, v74, v75
	v_cvt_pk_bf16_f32 v82, v76, v77
	v_cvt_pk_bf16_f32 v83, v78, v79
	global_store_dwordx4 v84, v[80:83], s[12:13]
	s_add_u32 s12, s12, 0x4000
	s_addc_u32 s13, s13, 0
	ds_read2_b32 v[72:73], v36 offset0:16 offset1:49
	ds_read2_b32 v[74:75], v36 offset0:82 offset1:115
	ds_read2_b32 v[76:77], v36 offset0:148 offset1:181
	ds_read2_b32 v[78:79], v36 offset0:214 offset1:247
	s_waitcnt lgkmcnt(0)
	v_cvt_pk_bf16_f32 v80, v72, v73
	v_cvt_pk_bf16_f32 v81, v74, v75
	v_cvt_pk_bf16_f32 v82, v76, v77
	v_cvt_pk_bf16_f32 v83, v78, v79
	global_store_dwordx4 v84, v[80:83], s[12:13]
	s_add_u32 s12, s12, 0x4000
	s_addc_u32 s13, s13, 0
	ds_read2_b32 v[72:73], v36 offset0:24 offset1:57
	ds_read2_b32 v[74:75], v36 offset0:90 offset1:123
	ds_read2_b32 v[76:77], v36 offset0:156 offset1:189
	ds_read2_b32 v[78:79], v36 offset0:222 offset1:255
	s_waitcnt lgkmcnt(0)
	v_cvt_pk_bf16_f32 v80, v72, v73
	v_cvt_pk_bf16_f32 v81, v74, v75
	v_cvt_pk_bf16_f32 v82, v76, v77
	v_cvt_pk_bf16_f32 v83, v78, v79
	global_store_dwordx4 v84, v[80:83], s[12:13]
	s_branch .Ltr2_next
; #define LAS __attribute__((address_space(3)))
; __device__ __forceinline__ unsigned pk2(float lo, float hi) { f32x2v v = {lo, hi}; b16x2v b = __builtin_convertvector(v, b16x2v); return __builtin_bit_cast(unsigned, b); }
;     __device__ __forceinline__ bf16_t* Wout_t() const { return (bf16_t*)(ws + WS_WOUT); }
; template <int MODE>
; __device__ __forceinline__ void tr_item(const float* __restrict__ W, int N, bf16_t* WT, int ldk, int row_off, LAS float* scr, int kb, int nb, int lane,
;                                         const float* g, const float* b, float* c1, float* c2) {
;     const int k0 = 64 * kb, n0 = 32 * nb;
;     float tv[32];
; #pragma unroll
;     for (int i = 0; i < 32; ++i) tv[i] = __builtin_nontemporal_load(W + (size_t)(k0 + 2 * i + (lane >> 5)) * N + n0 + (lane & 31));
; #pragma unroll
;     for (int i = 0; i < 32; ++i) scr[(2 * i + (lane >> 5)) * 33 + (lane & 31)] = tv[i];
;     asm volatile("s_waitcnt lgkmcnt(0)" ::: "memory");
;     if (MODE == 2) {
;         const float* vec = (lane < 32) ? g : b; float s = 0.f;
; #pragma unroll 8
;         for (int k = 0; k < 64; ++k) s += vec[k0 + k] * scr[k * 33 + (lane & 31)];
;         atomicAdd(((lane < 32) ? c1 : c2) + n0 + (lane & 31), s);
;     }
;     const int c = lane & 7;
;     float gs[8];
; #pragma unroll
;     for (int i = 0; i < 8; ++i) gs[i] = (MODE == 2) ? g[k0 + 8 * c + i] : 1.0f;
; #pragma unroll
;     for (int j = 0; j < 4; ++j) { const int n = (lane >> 3) + 8 * j; const LAS float* s = scr + (8 * c) * 33 + n;
;         u32x4 o; o.x = pk2(s[0 * 33] * gs[0], s[1 * 33] * gs[1]); o.y = pk2(s[2 * 33] * gs[2], s[3 * 33] * gs[3]); o.z = pk2(s[4 * 33] * gs[4], s[5 * 33] * gs[5]); o.w = pk2(s[6 * 33] * gs[6], s[7 * 33] * gs[7]);
;         const int dr = (MODE == 1) ? win_dest(n0 + n) : (n0 + n);
;         *(u32x4*)(WT + (size_t)(row_off + dr) * ldk + k0 + 8 * c) = o; }
; __device__ __forceinline__ void p0_prologue(const Args& p, LAS unsigned char* lds, int G, int bid, int tid) {
;     ...
;         if (r < I_OUT) { tr_item<0>(p.w_out(), DM, p.Wout_t(), DM, 0, scr, r / 32, r % 32, lane, nullptr, nullptr, nullptr, nullptr); continue; } r -= I_OUT;
.Ltr2_wout:
	s_sub_u32 s66, s10, 0xa00
	s_lshr_b32 s0, s66, 5
	s_and_b32 s1, s66, 31
	s_mul_i32 s12, s0, 0x40000
	s_lshl_b32 s13, s1, 7
	s_add_u32 s12, s12, s13
	s_add_u32 s12, s64, s12
	s_addc_u32 s13, s65, 0
	global_load_dword v40, v34, s[12:13] nt
	s_add_u32 s12, s12, 0x2000
	s_addc_u32 s13, s13, 0
	global_load_dword v41, v34, s[12:13] nt
	s_add_u32 s12, s12, 0x2000
	s_addc_u32 s13, s13, 0
	global_load_dword v42, v34, s[12:13] nt
	s_add_u32 s12, s12, 0x2000
	s_addc_u32 s13, s13, 0
	global_load_dword v43, v34, s[12:13] nt
	s_add_u32 s12, s12, 0x2000
	s_addc_u32 s13, s13, 0
	global_load_dword v44, v34, s[12:13] nt
	s_add_u32 s12, s12, 0x2000
	s_addc_u32 s13, s13, 0
	global_load_dword v45, v34, s[12:13] nt
	s_add_u32 s12, s12, 0x2000
	s_addc_u32 s13, s13, 0
	global_load_dword v46, v34, s[12:13] nt
	s_add_u32 s12, s12, 0x2000
	s_addc_u32 s13, s13, 0
	global_load_dword v47, v34, s[12:13] nt
	s_add_u32 s12, s12, 0x2000
	s_addc_u32 s13, s13, 0
	global_load_dword v48, v34, s[12:13] nt
	s_add_u32 s12, s12, 0x2000
	s_addc_u32 s13, s13, 0
	global_load_dword v49, v34, s[12:13] nt
	s_add_u32 s12, s12, 0x2000
	s_addc_u32 s13, s13, 0
	global_load_dword v50, v34, s[12:13] nt
	s_add_u32 s12, s12, 0x2000
	s_addc_u32 s13, s13, 0
	global_load_dword v51, v34, s[12:13] nt
	s_add_u32 s12, s12, 0x2000
	s_addc_u32 s13, s13, 0
	global_load_dword v52, v34, s[12:13] nt
	s_add_u32 s12, s12, 0x2000
	s_addc_u32 s13, s13, 0
	global_load_dword v53, v34, s[12:13] nt
	s_add_u32 s12, s12, 0x2000
	s_addc_u32 s13, s13, 0
	global_load_dword v54, v34, s[12:13] nt
	s_add_u32 s12, s12, 0x2000
	s_addc_u32 s13, s13, 0
	global_load_dword v55, v34, s[12:13] nt
	s_add_u32 s12, s12, 0x2000
	s_addc_u32 s13, s13, 0
	global_load_dword v56, v34, s[12:13] nt
	s_add_u32 s12, s12, 0x2000
	s_addc_u32 s13, s13, 0
	global_load_dword v57, v34, s[12:13] nt
	s_add_u32 s12, s12, 0x2000
	s_addc_u32 s13, s13, 0
	global_load_dword v58, v34, s[12:13] nt
	s_add_u32 s12, s12, 0x2000
	s_addc_u32 s13, s13, 0
	global_load_dword v59, v34, s[12:13] nt
	s_add_u32 s12, s12, 0x2000
	s_addc_u32 s13, s13, 0
	global_load_dword v60, v34, s[12:13] nt
	s_add_u32 s12, s12, 0x2000
	s_addc_u32 s13, s13, 0
	global_load_dword v61, v34, s[12:13] nt
	s_add_u32 s12, s12, 0x2000
	s_addc_u32 s13, s13, 0
	global_load_dword v62, v34, s[12:13] nt
	s_add_u32 s12, s12, 0x2000
	s_addc_u32 s13, s13, 0
	global_load_dword v63, v34, s[12:13] nt
	s_add_u32 s12, s12, 0x2000
	s_addc_u32 s13, s13, 0
	global_load_dword v64, v34, s[12:13] nt
	s_add_u32 s12, s12, 0x2000
	s_addc_u32 s13, s13, 0
	global_load_dword v65, v34, s[12:13] nt
	s_add_u32 s12, s12, 0x2000
	s_addc_u32 s13, s13, 0
	global_load_dword v66, v34, s[12:13] nt
	s_add_u32 s12, s12, 0x2000
	s_addc_u32 s13, s13, 0
	global_load_dword v67, v34, s[12:13] nt
	s_add_u32 s12, s12, 0x2000
	s_addc_u32 s13, s13, 0
	global_load_dword v68, v34, s[12:13] nt
	s_add_u32 s12, s12, 0x2000
	s_addc_u32 s13, s13, 0
	global_load_dword v69, v34, s[12:13] nt
	s_add_u32 s12, s12, 0x2000
	s_addc_u32 s13, s13, 0
	global_load_dword v70, v34, s[12:13] nt
	s_add_u32 s12, s12, 0x2000
	s_addc_u32 s13, s13, 0
	global_load_dword v71, v34, s[12:13] nt
	s_mul_i32 s12, s1, 0x10000
	s_lshl_b32 s13, s0, 7
	s_add_u32 s12, s12, s13
	s_add_u32 s12, s12, 0x900000
	s_add_u32 s12, s58, s12
	s_addc_u32 s13, s59, 0
	s_waitcnt vmcnt(31)
	ds_write_b32 v35, v40
	s_waitcnt vmcnt(30)
	ds_write_b32 v35, v41 offset:264
	s_waitcnt vmcnt(29)
	ds_write_b32 v35, v42 offset:528
	s_waitcnt vmcnt(28)
	ds_write_b32 v35, v43 offset:792
	s_waitcnt vmcnt(27)
	ds_write_b32 v35, v44 offset:1056
	s_waitcnt vmcnt(26)
	ds_write_b32 v35, v45 offset:1320
	s_waitcnt vmcnt(25)
	ds_write_b32 v35, v46 offset:1584
	s_waitcnt vmcnt(24)
	ds_write_b32 v35, v47 offset:1848
	s_waitcnt vmcnt(23)
	ds_write_b32 v35, v48 offset:2112
	s_waitcnt vmcnt(22)
	ds_write_b32 v35, v49 offset:2376
	s_waitcnt vmcnt(21)
	ds_write_b32 v35, v50 offset:2640
	s_waitcnt vmcnt(20)
	ds_write_b32 v35, v51 offset:2904
	s_waitcnt vmcnt(19)
	ds_write_b32 v35, v52 offset:3168
	s_waitcnt vmcnt(18)
	ds_write_b32 v35, v53 offset:3432
	s_waitcnt vmcnt(17)
	ds_write_b32 v35, v54 offset:3696
	s_waitcnt vmcnt(16)
	ds_write_b32 v35, v55 offset:3960
	s_waitcnt vmcnt(15)
	ds_write_b32 v35, v56 offset:4224
	s_waitcnt vmcnt(14)
	ds_write_b32 v35, v57 offset:4488
	s_waitcnt vmcnt(13)
	ds_write_b32 v35, v58 offset:4752
	s_waitcnt vmcnt(12)
	ds_write_b32 v35, v59 offset:5016
	s_waitcnt vmcnt(11)
	ds_write_b32 v35, v60 offset:5280
	s_waitcnt vmcnt(10)
	ds_write_b32 v35, v61 offset:5544
	s_waitcnt vmcnt(9)
	ds_write_b32 v35, v62 offset:5808
	s_waitcnt vmcnt(8)
	ds_write_b32 v35, v63 offset:6072
	s_waitcnt vmcnt(7)
	ds_write_b32 v35, v64 offset:6336
	s_waitcnt vmcnt(6)
	ds_write_b32 v35, v65 offset:6600
	s_waitcnt vmcnt(5)
	ds_write_b32 v35, v66 offset:6864
	s_waitcnt vmcnt(4)
	ds_write_b32 v35, v67 offset:7128
	s_waitcnt vmcnt(3)
	ds_write_b32 v35, v68 offset:7392
	s_waitcnt vmcnt(2)
	ds_write_b32 v35, v69 offset:7656
	s_waitcnt vmcnt(1)
	ds_write_b32 v35, v70 offset:7920
	s_waitcnt vmcnt(0)
	ds_write_b32 v35, v71 offset:8184
	s_waitcnt lgkmcnt(0)
	ds_read2_b32 v[72:73], v36 offset1:33
	ds_read2_b32 v[74:75], v36 offset0:66 offset1:99
	ds_read2_b32 v[76:77], v36 offset0:132 offset1:165
	ds_read2_b32 v[78:79], v36 offset0:198 offset1:231
	s_waitcnt lgkmcnt(0)
	v_cvt_pk_bf16_f32 v80, v72, v73
	v_cvt_pk_bf16_f32 v81, v74, v75
	v_cvt_pk_bf16_f32 v82, v76, v77
	v_cvt_pk_bf16_f32 v83, v78, v79
	global_store_dwordx4 v84, v[80:83], s[12:13]
	s_add_u32 s12, s12, 0x4000
	s_addc_u32 s13, s13, 0
	ds_read2_b32 v[72:73], v36 offset0:8 offset1:41
	ds_read2_b32 v[74:75], v36 offset0:74 offset1:107
	ds_read2_b32 v[76:77], v36 offset0:140 offset1:173
	ds_read2_b32 v[78:79], v36 offset0:206 offset1:239
	s_waitcnt lgkmcnt(0)
	v_cvt_pk_bf16_f32 v80, v72, v73
	v_cvt_pk_bf16_f32 v81, v74, v75
	v_cvt_pk_bf16_f32 v82, v76, v77
	v_cvt_pk_bf16_f32 v83, v78, v79
	global_store_dwordx4 v84, v[80:83], s[12:13]
	s_add_u32 s12, s12, 0x4000
	s_addc_u32 s13, s13, 0
	ds_read2_b32 v[72:73], v36 offset0:16 offset1:49
	ds_read2_b32 v[74:75], v36 offset0:82 offset1:115
	ds_read2_b32 v[76:77], v36 offset0:148 offset1:181
	ds_read2_b32 v[78:79], v36 offset0:214 offset1:247
	s_waitcnt lgkmcnt(0)
	v_cvt_pk_bf16_f32 v80, v72, v73
	v_cvt_pk_bf16_f32 v81, v74, v75
	v_cvt_pk_bf16_f32 v82, v76, v77
	v_cvt_pk_bf16_f32 v83, v78, v79
	global_store_dwordx4 v84, v[80:83], s[12:13]
	s_add_u32 s12, s12, 0x4000
	s_addc_u32 s13, s13, 0
	ds_read2_b32 v[72:73], v36 offset0:24 offset1:57
	ds_read2_b32 v[74:75], v36 offset0:90 offset1:123
	ds_read2_b32 v[76:77], v36 offset0:156 offset1:189
	ds_read2_b32 v[78:79], v36 offset0:222 offset1:255
	s_waitcnt lgkmcnt(0)
	v_cvt_pk_bf16_f32 v80, v72, v73
	v_cvt_pk_bf16_f32 v81, v74, v75
	v_cvt_pk_bf16_f32 v82, v76, v77
	v_cvt_pk_bf16_f32 v83, v78, v79
	global_store_dwordx4 v84, v[80:83], s[12:13]
.Ltr2_next:
	s_add_u32 s10, s10, s11
	s_branch .Ltr2_loop
